# natten: all 16 q/k gain loads issued with the unit's first loads (slots v184-v249), copies at the old load sites
# baseline (speedup 1.0000x reference)
.LBB0_504:
	s_ashr_i32 s36, s63, 9
	s_lshl_b32 s37, s63, 2
	s_bfe_u32 s81, s63, 0x50004
	s_and_b32 s80, s37, 60
	s_ashr_i32 s37, s36, 31
	s_lshl_b64 s[58:59], s[36:37], 12
	s_lshl_b32 s62, s81, 7
	v_mov_b32_e32 v3, s59
	v_or_b32_e32 v2, s58, v114
	v_or_b32_e32 v4, s62, v114
	v_lshlrev_b64 v[2:3], 14, v[2:3]
	v_lshlrev_b32_e32 v116, 15, v4
	v_lshl_add_u64 v[2:3], s[40:41], 0, v[2:3]
	s_lshl_b32 s46, s81, 8
	v_lshl_add_u64 v[4:5], s[42:43], 0, v[116:117]
	s_lshl_b64 s[52:53], s[36:37], 13
	v_sub_u32_e64 v12, s80, 4 clamp
	v_lshl_add_u64 v[2:3], v[2:3], 0, s[46:47]
	v_mov_b32_e32 v135, v117
	v_lshl_add_u64 v[4:5], v[4:5], 0, s[52:53]
	v_lshl_add_u64 v[2:3], v[2:3], 0, v[134:135]
	v_lshl_add_u64 v[10:11], v[4:5], 0, v[134:135]
	v_lshlrev_b32_e32 v4, 20, v12
	v_mov_b32_e32 v5, v117
	v_or_b32_e32 v146, s80, v1
	v_lshl_add_u64 v[2:3], v[2:3], 0, v[4:5]
	s_mov_b64 s[82:83], 0x2000
	v_lshl_add_u64 v[6:7], v[2:3], 0, s[82:83]
	s_movk_i32 s82, 0x2000
	v_lshl_or_b32 v18, v146, 6, s58
	v_add_co_u32_e32 v2, vcc, s82, v2
	v_lshlrev_b32_e32 v12, 7, v12
	v_mov_b32_e32 v13, v117
	v_or_b32_e32 v36, v18, v162
	v_addc_co_u32_e32 v3, vcc, 0, v3, vcc
	v_lshl_add_u64 v[10:11], v[10:11], 0, v[12:13]
	s_mov_b32 s82, 0x200000
	v_mov_b32_e32 v141, s59
	v_or_b32_e32 v140, v36, v126
	v_or_b32_e32 v142, v36, v128
	v_mov_b32_e32 v143, s59
	v_add_co_u32_e32 v14, vcc, s82, v10
	v_lshl_add_u64 v[34:35], v[118:119], 0, s[46:47]
	v_lshlrev_b64 v[138:139], 14, v[140:141]
	v_lshlrev_b64 v[136:137], 14, v[142:143]
	v_addc_co_u32_e32 v15, vcc, 0, v11, vcc
	v_lshl_add_u64 v[22:23], v[34:35], 0, v[138:139]
	v_lshl_add_u64 v[38:39], v[34:35], 0, v[136:137]
	global_load_dwordx4 v[2:5], v[2:3], off
	s_nop 0
	global_load_dwordx4 v[6:9], v[6:7], off offset:128
	s_nop 0
	global_load_dwordx4 v[10:13], v[10:11], off
	s_nop 0
	global_load_dwordx4 v[14:17], v[14:15], off
	s_nop 0
	global_load_dwordx4 v[30:33], v[22:23], off
	global_load_dwordx4 v[26:29], v[22:23], off offset:64
	global_load_dwordx4 v[18:21], v[22:23], off offset:128
	s_nop 0
	global_load_dwordx4 v[22:25], v[22:23], off offset:192
	s_nop 0
	global_load_dwordx4 v[46:49], v[38:39], off
	global_load_dwordx4 v[42:45], v[38:39], off offset:64
	global_load_dwordx4 v[34:37], v[38:39], off offset:128
	s_nop 0
	global_load_dwordx4 v[38:41], v[38:39], off offset:192
	global_load_dwordx4 v[184:187], v[120:121], off offset:16
	global_load_dwordx4 v[188:191], v[120:121], off
	global_load_dwordx4 v[192:195], v[122:123], off offset:16
	global_load_dwordx4 v[196:199], v[122:123], off
	global_load_dwordx4 v[200:203], v[120:121], off offset:144
	global_load_dwordx4 v[204:207], v[120:121], off offset:128
	global_load_dwordx4 v[208:211], v[122:123], off offset:144
	global_load_dwordx4 v[212:215], v[122:123], off offset:128
	global_load_dwordx4 v[216:219], v[120:121], off offset:272
	global_load_dwordx4 v[220:223], v[120:121], off offset:256
	global_load_dwordx4 v[224:227], v[122:123], off offset:272
	global_load_dwordx4 v[228:231], v[122:123], off offset:256
	global_load_dwordx4 v[232:235], v[120:121], off offset:400
	global_load_dwordx4 v[238:241], v[120:121], off offset:384
	global_load_dwordx4 v[242:245], v[122:123], off offset:400
	global_load_dwordx4 v[246:249], v[122:123], off offset:384
	v_mov_b32_e32 v50, 0
	s_and_saveexec_b64 s[58:59], s[84:85]
	s_cbranch_execz .LBB0_506
	s_mulk_i32 s81, 0x1d1
	v_readlane_b32 s0, v254, 7
	v_add_lshl_u32 v50, s81, v0, 2
	v_readlane_b32 s6, v254, 13
	v_readlane_b32 s7, v254, 14
	v_readlane_b32 s1, v254, 8
	v_readlane_b32 s2, v254, 9
	v_readlane_b32 s3, v254, 10
	v_readlane_b32 s4, v254, 11
	v_readlane_b32 s5, v254, 12
	global_load_dword v50, v50, s[6:7]
	v_readlane_b32 s8, v254, 15
	v_readlane_b32 s9, v254, 16
	v_readlane_b32 s10, v254, 17
	v_readlane_b32 s11, v254, 18
	v_readlane_b32 s12, v254, 19
	v_readlane_b32 s13, v254, 20
	v_readlane_b32 s14, v254, 21
	v_readlane_b32 s15, v254, 22

.LBB0_508:
	s_or_b64 exec, exec, s[58:59]
	s_waitcnt vmcnt(0)
	v_sub_u32_e64 v50, s80, 1 clamp
	v_and_b32_e32 v55, 0xffff0000, v31
	v_and_b32_e32 v59, 0xffff0000, v30
	v_and_b32_e32 v58, 0xffff0000, v32
	v_readfirstlane_b32 s58, v50
	v_lshlrev_b32_e32 v54, 16, v31
	v_mul_f32_e32 v50, v55, v55
	v_lshlrev_b32_e32 v57, 16, v30
	v_lshlrev_b32_e32 v56, 16, v32
	v_pk_mul_f32 v[30:31], v[58:59], v[58:59]
	v_pk_fma_f32 v[50:51], v[54:55], v[54:55], v[50:51] op_sel_hi:[1,1,0]
	v_pk_fma_f32 v[30:31], v[56:57], v[56:57], v[30:31]
	v_and_b32_e32 v53, 0xffff0000, v29
	v_pk_add_f32 v[50:51], v[30:31], v[50:51] op_sel:[1,0] op_sel_hi:[0,1]
	v_pk_add_f32 v[72:73], v[30:31], v[50:51]
	v_and_b32_e32 v51, 0xffff0000, v27
	v_and_b32_e32 v50, 0xffff0000, v26
	v_lshlrev_b32_e32 v31, 16, v27
	v_lshlrev_b32_e32 v30, 16, v26
	v_pk_mul_f32 v[26:27], v[50:51], v[50:51]
	v_and_b32_e32 v52, 0xffff0000, v28
	v_lshlrev_b32_e32 v60, 16, v33
	v_and_b32_e32 v61, 0xffff0000, v33
	v_pk_fma_f32 v[26:27], v[30:31], v[30:31], v[26:27]
	v_lshlrev_b32_e32 v33, 16, v29
	v_lshlrev_b32_e32 v32, 16, v28
	v_pk_mul_f32 v[28:29], v[52:53], v[52:53]
	v_pk_add_f32 v[26:27], v[26:27], v[26:27] op_sel:[0,1] op_sel_hi:[1,0]
	v_pk_fma_f32 v[74:75], v[32:33], v[32:33], v[28:29]
	v_lshlrev_b32_e32 v28, 16, v19
	v_pk_add_f32 v[76:77], v[74:75], v[26:27]
	v_and_b32_e32 v27, 0xffff0000, v18
	v_lshlrev_b32_e32 v26, 16, v18
	v_and_b32_e32 v29, 0xffff0000, v19
	v_lshlrev_b32_e32 v98, 16, v23
	v_lshlrev_b32_e32 v70, 16, v20
	v_and_b32_e32 v68, 0xffff0000, v20
	v_pk_mov_b32 v[18:19], v[20:21], v[24:25] op_sel:[1,0]
	v_mul_f32_e32 v20, v27, v27
	v_and_b32_e32 v97, 0xffff0000, v23
	v_mul_f32_e32 v23, v98, v98
	v_lshlrev_b32_e32 v71, 16, v22
	v_and_b32_e32 v69, 0xffff0000, v22
	v_lshlrev_b32_e32 v66, 16, v21
	v_pk_fma_f32 v[20:21], v[26:27], v[26:27], v[20:21] op_sel_hi:[1,1,0]
	v_mul_f32_e32 v22, v29, v29
	v_mul_f32_e32 v62, v97, v97
	v_mov_b32_e32 v21, v23
	v_pk_fma_f32 v[22:23], v[28:29], v[28:29], v[22:23] op_sel_hi:[1,1,0]
	v_and_b32_e32 v65, 0xffff0000, v19
	v_and_b32_e32 v64, 0xffff0000, v18
	v_pk_mul_f32 v[18:19], v[68:69], v[68:69]
	v_mov_b32_e32 v23, v62
	v_pk_fma_f32 v[18:19], v[70:71], v[70:71], v[18:19]
	v_pk_add_f32 v[20:21], v[20:21], v[22:23]
	v_lshlrev_b32_e32 v67, 16, v24
	v_pk_add_f32 v[18:19], v[18:19], v[20:21]
	v_pk_mul_f32 v[20:21], v[64:65], v[64:65]
	v_lshlrev_b32_e32 v63, 16, v25
	v_pk_fma_f32 v[20:21], v[66:67], v[66:67], v[20:21]
	v_mov_b32_e32 v22, v72
	v_pk_add_f32 v[18:19], v[20:21], v[18:19]
	v_mul_f32_e32 v20, v61, v61
	v_pk_fma_f32 v[20:21], v[60:61], v[60:61], v[20:21] op_sel_hi:[1,1,0]
	v_mov_b32_e32 v23, v63
	v_mov_b32_e32 v62, v20
	v_and_b32_e32 v96, 0xffff0000, v25
	v_pk_add_f32 v[20:21], v[20:21], v[72:73]
	v_pk_mul_f32 v[22:23], v[62:63], v[22:23]
	v_mul_f32_e32 v78, v96, v96
	v_mov_b32_e32 v21, v23
	v_pk_add_f32 v[22:23], v[74:75], v[76:77] op_sel:[1,0] op_sel_hi:[0,1]
	v_mov_b32_e32 v23, v78
	v_pk_add_f32 v[20:21], v[20:21], v[22:23]
	v_lshlrev_b32_e32 v108, 16, v39
	v_pk_add_f32 v[18:19], v[20:21], v[18:19]
	v_and_b32_e32 v109, 0xffff0000, v39
	v_add_f32_e32 v18, v18, v19
	ds_bpermute_b32 v19, v173, v18
	v_lshlrev_b32_e32 v39, 16, v41
	v_lshlrev_b32_e32 v99, 16, v38
	v_and_b32_e32 v101, 0xffff0000, v38
	v_mul_f32_e32 v106, v108, v108
	s_waitcnt lgkmcnt(0)
	v_add_f32_e32 v18, v18, v19
	ds_bpermute_b32 v19, v174, v18
	v_mul_f32_e32 v111, v109, v109
	v_and_b32_e32 v100, 0xffff0000, v36
	v_pk_mov_b32 v[102:103], v[36:37], v[40:41] op_sel:[1,0]
	v_and_b32_e32 v110, 0xffff0000, v41
	s_waitcnt lgkmcnt(0)
	v_add_f32_e32 v18, v18, v19
	v_fmamk_f32 v18, v18, 0x3c000000, v179
	v_cmp_gt_f32_e32 vcc, s60, v18
	v_mul_f32_e32 v19, 0x4b800000, v18
	v_lshlrev_b32_e32 v41, 16, v40
	v_cndmask_b32_e32 v18, v18, v19, vcc
	v_rsq_f32_e32 v18, v18
	v_lshlrev_b32_e32 v40, 16, v37
	v_and_b32_e32 v37, 0xffff0000, v103
	v_mul_f32_e32 v112, v110, v110
	v_mul_f32_e32 v19, 0x45800000, v18
	v_cndmask_b32_e32 v18, v18, v19, vcc
	v_mul_f32_e32 v62, 0x3db504f3, v18
	v_mov_b64_e32 v[18:19], v[184:185]
	v_mov_b64_e32 v[20:21], v[186:187]
	v_mov_b64_e32 v[22:23], v[188:189]
	v_mov_b64_e32 v[24:25], v[190:191]
	v_mov_b64_e32 v[80:81], v[192:193]
	v_mov_b64_e32 v[82:83], v[194:195]
	v_mov_b64_e32 v[72:73], v[196:197]
	v_mov_b64_e32 v[74:75], v[198:199]
	v_mul_f32_e32 v26, v62, v26
	v_mul_f32_e32 v27, v62, v27
	s_min_u32 s58, s58, 56
	s_sub_i32 s58, s58, s46
	v_mov_b32_e32 v145, 0
	s_cmp_lt_i32 s58, -11
	v_mov_b32_e32 v144, v145
	v_mov_b32_e32 v113, v145
	s_waitcnt vmcnt(0)
	v_pk_mul_f32 v[76:77], v[24:25], v[74:75]
	v_pk_mul_f32 v[78:79], v[22:23], v[72:73]
	v_pk_mul_f32 v[74:75], v[18:19], v[80:81]
	v_mul_f32_e32 v18, v62, v57
	v_mul_f32_e32 v19, v62, v59
	v_mul_f32_e32 v18, v78, v18
	v_mul_f32_e32 v19, v79, v19
	v_pk_mul_f32 v[72:73], v[20:21], v[82:83]
	v_cvt_pk_bf16_f32 v18, v18, v19
	v_mul_f32_e32 v19, v62, v54
	v_mul_f32_e32 v20, v62, v55
	v_mul_f32_e32 v19, v76, v19
	v_mul_f32_e32 v20, v77, v20
	v_cvt_pk_bf16_f32 v19, v19, v20
	v_mul_f32_e32 v20, v62, v56
	v_mul_f32_e32 v21, v62, v58
	v_mul_f32_e32 v20, v74, v20
	v_mul_f32_e32 v21, v75, v21
	v_cvt_pk_bf16_f32 v20, v20, v21
	v_mul_f32_e32 v21, v62, v60
	v_mul_f32_e32 v22, v62, v61
	v_mul_f32_e32 v21, v72, v21
	v_mul_f32_e32 v22, v73, v22
	v_cvt_pk_bf16_f32 v21, v21, v22
	v_mov_b64_e32 v[22:23], v[200:201]
	v_mov_b64_e32 v[24:25], v[202:203]
	v_mov_b64_e32 v[54:55], v[204:205]
	v_mov_b64_e32 v[56:57], v[206:207]
	v_mov_b64_e32 v[58:59], v[208:209]
	v_mov_b64_e32 v[60:61], v[210:211]
	v_mov_b64_e32 v[80:81], v[212:213]
	v_mov_b64_e32 v[82:83], v[214:215]
	s_waitcnt vmcnt(0)
	v_pk_mul_f32 v[84:85], v[56:57], v[82:83]
	v_pk_mul_f32 v[86:87], v[54:55], v[80:81]
	v_pk_mul_f32 v[82:83], v[22:23], v[58:59]
	v_mul_f32_e32 v22, v62, v30
	v_mul_f32_e32 v23, v62, v50
	v_mul_f32_e32 v22, v22, v86
	v_mul_f32_e32 v23, v23, v87
	v_pk_mul_f32 v[80:81], v[24:25], v[60:61]
	v_cvt_pk_bf16_f32 v22, v22, v23
	v_mul_f32_e32 v23, v62, v31
	v_mul_f32_e32 v24, v62, v51
	v_mul_f32_e32 v23, v23, v84
	v_mul_f32_e32 v24, v24, v85
	v_cvt_pk_bf16_f32 v23, v23, v24
	v_mul_f32_e32 v24, v62, v32
	v_mul_f32_e32 v25, v62, v52
	v_mul_f32_e32 v24, v24, v82
	v_mul_f32_e32 v25, v25, v83
	v_cvt_pk_bf16_f32 v24, v24, v25
	v_mul_f32_e32 v25, v62, v33
	v_mul_f32_e32 v30, v62, v53
	v_mul_f32_e32 v25, v25, v80
	v_mul_f32_e32 v30, v30, v81
	v_cvt_pk_bf16_f32 v25, v25, v30
	v_mov_b64_e32 v[30:31], v[216:217]
	v_mov_b64_e32 v[32:33], v[218:219]
	v_mov_b64_e32 v[50:51], v[220:221]
	v_mov_b64_e32 v[52:53], v[222:223]
	v_mov_b64_e32 v[54:55], v[224:225]
	v_mov_b64_e32 v[56:57], v[226:227]
	v_mov_b64_e32 v[58:59], v[228:229]
	v_mov_b64_e32 v[60:61], v[230:231]
	s_waitcnt vmcnt(1)
	v_pk_mul_f32 v[90:91], v[30:31], v[54:55]
	s_waitcnt vmcnt(0)
	v_pk_mul_f32 v[94:95], v[50:51], v[58:59]
	v_pk_mul_f32 v[92:93], v[52:53], v[60:61]
	v_mul_f32_e32 v26, v26, v94
	v_mul_f32_e32 v27, v27, v95
	v_cvt_pk_bf16_f32 v26, v26, v27
	v_mul_f32_e32 v27, v62, v28
	v_mul_f32_e32 v28, v62, v29
	v_mul_f32_e32 v27, v27, v92
	v_mul_f32_e32 v28, v28, v93
	v_cvt_pk_bf16_f32 v27, v27, v28
	v_mul_f32_e32 v28, v62, v70
	v_mul_f32_e32 v29, v62, v68
	v_mul_f32_e32 v28, v28, v90
	v_mul_f32_e32 v29, v29, v91
	v_pk_mul_f32 v[88:89], v[32:33], v[56:57]
	v_cvt_pk_bf16_f32 v28, v28, v29
	v_mul_f32_e32 v29, v62, v66
	v_mul_f32_e32 v30, v62, v64
	v_mul_f32_e32 v29, v29, v88
	v_mul_f32_e32 v30, v30, v89
	v_cvt_pk_bf16_f32 v29, v29, v30
	v_mov_b64_e32 v[30:31], v[232:233]
	v_mov_b64_e32 v[32:33], v[234:235]
	v_mov_b64_e32 v[54:55], v[238:239]
	v_mov_b64_e32 v[56:57], v[240:241]
	v_mov_b64_e32 v[50:51], v[242:243]
	v_mov_b64_e32 v[52:53], v[244:245]
	v_mov_b64_e32 v[58:59], v[246:247]
	v_mov_b64_e32 v[60:61], v[248:249]
	v_lshlrev_b32_e32 v68, 16, v44
	v_and_b32_e32 v44, 0xffff0000, v44
	s_barrier
	s_waitcnt vmcnt(1)
	v_pk_mul_f32 v[50:51], v[30:31], v[50:51]
	s_waitcnt vmcnt(0)
	v_pk_mul_f32 v[58:59], v[54:55], v[58:59]
	v_mul_f32_e32 v30, v62, v71
	v_mul_f32_e32 v31, v62, v69
	v_mul_f32_e32 v30, v30, v58
	v_mul_f32_e32 v31, v31, v59
	v_pk_mul_f32 v[60:61], v[56:57], v[60:61]
	v_pk_mul_f32 v[52:53], v[32:33], v[52:53]
	v_cvt_pk_bf16_f32 v30, v30, v31
	v_mul_f32_e32 v31, v62, v98
	v_mul_f32_e32 v32, v62, v97
	v_mul_f32_e32 v31, v31, v60
	v_mul_f32_e32 v32, v32, v61
	v_cvt_pk_bf16_f32 v31, v31, v32
	v_mul_f32_e32 v32, v62, v67
	v_mul_f32_e32 v33, v62, v65
	v_mul_f32_e32 v32, v32, v50
	v_mul_f32_e32 v33, v33, v51
	v_cvt_pk_bf16_f32 v32, v32, v33
	v_mul_f32_e32 v33, v62, v63
	v_mul_f32_e32 v54, v62, v96
	v_and_b32_e32 v97, 0xffff0000, v34
	v_mul_f32_e32 v33, v33, v52
	v_mul_f32_e32 v54, v54, v53
	v_lshlrev_b32_e32 v56, 16, v47
	v_and_b32_e32 v57, 0xffff0000, v47
	v_lshlrev_b32_e32 v63, 16, v46
	v_and_b32_e32 v47, 0xffff0000, v46
	v_and_b32_e32 v46, 0xffff0000, v48
	v_lshlrev_b32_e32 v96, 16, v34
	v_lshlrev_b32_e32 v34, 16, v35
	v_and_b32_e32 v35, 0xffff0000, v35
	v_mul_f32_e32 v38, v97, v97
	v_cvt_pk_bf16_f32 v33, v33, v54
	v_mul_f32_e32 v54, v57, v57
	v_lshlrev_b32_e32 v62, 16, v48
	v_pk_mul_f32 v[64:65], v[46:47], v[46:47]
	v_pk_fma_f32 v[104:105], v[96:97], v[96:97], v[38:39] op_sel_hi:[1,1,0]
	v_mul_f32_e32 v38, v35, v35
	v_pk_fma_f32 v[54:55], v[56:57], v[56:57], v[54:55] op_sel_hi:[1,1,0]
	v_pk_fma_f32 v[64:65], v[62:63], v[62:63], v[64:65]
	v_mov_b32_e32 v105, v106
	v_pk_fma_f32 v[106:107], v[34:35], v[34:35], v[38:39] op_sel_hi:[1,1,0]
	v_pk_add_f32 v[54:55], v[64:65], v[54:55] op_sel:[1,0] op_sel_hi:[0,1]
	v_lshlrev_b32_e32 v98, 16, v36
	v_and_b32_e32 v36, 0xffff0000, v102
	v_pk_mul_f32 v[102:103], v[100:101], v[100:101]
	v_mov_b32_e32 v107, v111
	v_pk_add_f32 v[54:55], v[64:65], v[54:55]
	v_lshlrev_b32_e32 v65, 16, v43
	v_lshlrev_b32_e32 v64, 16, v42
	v_and_b32_e32 v43, 0xffff0000, v43
	v_and_b32_e32 v42, 0xffff0000, v42
	v_pk_fma_f32 v[102:103], v[98:99], v[98:99], v[102:103]
	v_pk_add_f32 v[104:105], v[104:105], v[106:107]
	v_lshlrev_b32_e32 v48, 16, v49
	v_and_b32_e32 v49, 0xffff0000, v49
	v_pk_mul_f32 v[66:67], v[42:43], v[42:43]
	v_lshlrev_b32_e32 v69, 16, v45
	v_and_b32_e32 v45, 0xffff0000, v45
	v_pk_add_f32 v[102:103], v[102:103], v[104:105]
	v_pk_mul_f32 v[104:105], v[36:37], v[36:37]
	v_pk_fma_f32 v[66:67], v[64:65], v[64:65], v[66:67]
	v_pk_mul_f32 v[70:71], v[44:45], v[44:45]
	v_pk_fma_f32 v[104:105], v[40:41], v[40:41], v[104:105]
	v_mul_f32_e32 v38, v49, v49
	v_pk_add_f32 v[66:67], v[66:67], v[66:67] op_sel:[0,1] op_sel_hi:[1,0]
	v_pk_fma_f32 v[70:71], v[68:69], v[68:69], v[70:71]
	v_pk_add_f32 v[102:103], v[104:105], v[102:103]
	v_pk_fma_f32 v[104:105], v[48:49], v[48:49], v[38:39] op_sel_hi:[1,1,0]
	v_pk_add_f32 v[66:67], v[70:71], v[66:67]
	v_mov_b32_e32 v38, v104
	v_mov_b32_e32 v106, v54
	v_mov_b32_e32 v107, v39
	v_pk_add_f32 v[54:55], v[104:105], v[54:55]
	v_pk_mul_f32 v[104:105], v[38:39], v[106:107]
	v_pk_add_f32 v[66:67], v[70:71], v[66:67] op_sel:[1,0] op_sel_hi:[0,1]
	v_mov_b32_e32 v55, v105
	v_mov_b32_e32 v67, v112
	v_pk_add_f32 v[54:55], v[54:55], v[66:67]
	v_mov_b32_e32 v105, v145
	v_pk_add_f32 v[54:55], v[54:55], v[102:103]
	v_mov_b32_e32 v104, v145
	v_add_f32_e32 v38, v54, v55
	ds_bpermute_b32 v54, v173, v38
	v_mov_b32_e32 v103, v145
	v_mov_b32_e32 v102, v145
	v_mov_b32_e32 v107, v145
	v_mov_b32_e32 v106, v145
	s_waitcnt lgkmcnt(0)
	v_add_f32_e32 v38, v38, v54
	ds_bpermute_b32 v54, v174, v38
	v_mov_b32_e32 v112, v145
	v_mov_b32_e32 v111, v145
	s_waitcnt lgkmcnt(0)
	v_add_f32_e32 v38, v38, v54
	v_fmamk_f32 v38, v38, 0x3c000000, v179
	v_cmp_gt_f32_e32 vcc, s60, v38
	v_mul_f32_e32 v54, 0x4b800000, v38
	s_nop 0
	v_cndmask_b32_e32 v38, v38, v54, vcc
	v_rsq_f32_e32 v38, v38
	s_nop 0
	v_mul_f32_e32 v54, 0x45800000, v38
	v_cndmask_b32_e32 v38, v38, v54, vcc
	v_mul_f32_e32 v38, 0x3db504f3, v38
	v_mul_f32_e32 v54, v38, v63
	v_mul_f32_e32 v47, v38, v47
	v_mul_f32_e32 v54, v78, v54
	v_mul_f32_e32 v47, v79, v47
	v_cvt_pk_bf16_f32 v54, v54, v47
	v_mul_f32_e32 v47, v38, v56
	v_mul_f32_e32 v55, v38, v57
	v_mul_f32_e32 v34, v38, v34
	v_mul_f32_e32 v47, v76, v47
	v_mul_f32_e32 v55, v77, v55
	v_mul_f32_e32 v46, v38, v46
	v_mul_f32_e32 v34, v92, v34
	v_mul_f32_e32 v35, v38, v35
	v_cvt_pk_bf16_f32 v55, v47, v55
	v_mul_f32_e32 v47, v38, v62
	v_mul_f32_e32 v46, v75, v46
	v_mul_f32_e32 v35, v93, v35
	v_cvt_pk_bf16_f32 v71, v34, v35
	v_mul_f32_e32 v34, v38, v98
	v_mul_f32_e32 v47, v74, v47
	v_cvt_pk_bf16_f32 v56, v47, v46
	v_mul_f32_e32 v46, v38, v48
	v_mul_f32_e32 v34, v90, v34
	v_mul_f32_e32 v35, v38, v100
	v_mul_f32_e32 v46, v72, v46
	v_mul_f32_e32 v35, v91, v35
	v_cvt_pk_bf16_f32 v72, v34, v35
	v_mul_f32_e32 v34, v38, v40
	v_mul_f32_e32 v47, v38, v49
	v_mul_f32_e32 v42, v38, v42
	v_mul_f32_e32 v34, v88, v34
	v_mul_f32_e32 v35, v38, v36
	v_mul_f32_e32 v47, v73, v47
	v_cvt_pk_bf16_f32 v57, v46, v47
	v_mul_f32_e32 v46, v38, v64
	v_mul_f32_e32 v42, v87, v42
	v_mul_f32_e32 v35, v89, v35
	v_cvt_pk_bf16_f32 v73, v34, v35
	v_mul_f32_e32 v34, v38, v99
	v_mul_f32_e32 v46, v86, v46
	v_cvt_pk_bf16_f32 v62, v46, v42
	v_mul_f32_e32 v42, v38, v65
	v_mul_f32_e32 v34, v58, v34
	v_mul_f32_e32 v35, v38, v101
	v_mul_f32_e32 v42, v84, v42
	v_mul_f32_e32 v43, v38, v43
	v_mul_f32_e32 v35, v59, v35
	v_cvt_pk_bf16_f32 v78, v34, v35
	v_mul_f32_e32 v34, v38, v108
	v_mul_f32_e32 v43, v85, v43
	v_cvt_pk_bf16_f32 v63, v42, v43
	v_mul_f32_e32 v42, v38, v68
	v_mul_f32_e32 v34, v60, v34
	v_mul_f32_e32 v35, v38, v109
	v_mul_f32_e32 v42, v82, v42
	v_mul_f32_e32 v43, v38, v44
	v_mul_f32_e32 v35, v61, v35
	v_cvt_pk_bf16_f32 v79, v34, v35
	v_mul_f32_e32 v34, v38, v41
	v_mul_f32_e32 v43, v83, v43
	v_cvt_pk_bf16_f32 v64, v42, v43
	v_mul_f32_e32 v42, v38, v69
	v_mul_f32_e32 v34, v50, v34
	v_mul_f32_e32 v35, v38, v37
	v_mul_f32_e32 v42, v80, v42
	v_mul_f32_e32 v43, v38, v45
	v_mul_f32_e32 v35, v51, v35
	v_cvt_pk_bf16_f32 v80, v34, v35
	v_mul_f32_e32 v34, v38, v39
	v_and_b32_e32 v47, 0xffff0000, v5
	v_and_b32_e32 v46, 0xffff0000, v4
	v_mul_f32_e32 v43, v81, v43
	v_cvt_pk_bf16_f32 v65, v42, v43
	v_mul_f32_e32 v42, v38, v96
	v_mul_f32_e32 v34, v52, v34
	v_mul_f32_e32 v35, v38, v110
	v_lshlrev_b32_e32 v45, 16, v5
	v_lshlrev_b32_e32 v44, 16, v4
	v_pk_mul_f32 v[48:49], v[46:47], v[46:47]
	v_mul_f32_e32 v42, v94, v42
	v_mul_f32_e32 v43, v38, v97
	v_mul_f32_e32 v35, v53, v35
	v_cvt_pk_bf16_f32 v81, v34, v35
	v_lshlrev_b32_e32 v34, 16, v2
	v_lshlrev_b32_e32 v38, 16, v3
	v_pk_fma_f32 v[48:49], v[44:45], v[44:45], v[48:49]
	v_mul_f32_e32 v43, v95, v43
	v_cvt_pk_bf16_f32 v70, v42, v43
	v_and_b32_e32 v35, 0xffff0000, v2
	v_mul_f32_e32 v36, v34, v34
	v_and_b32_e32 v39, 0xffff0000, v3
	v_mul_f32_e32 v42, v38, v38
	v_pk_add_f32 v[48:49], v[48:49], v[48:49] op_sel_hi:[0,1]
	v_lshlrev_b32_e32 v50, 16, v6
	v_lshlrev_b32_e32 v40, 16, v8
	v_pk_fma_f32 v[36:37], v[34:35], v[34:35], v[36:37] op_sel_hi:[1,1,0]
	v_pk_fma_f32 v[42:43], v[38:39], v[38:39], v[42:43] op_sel_hi:[1,1,0]
	v_and_b32_e32 v51, 0xffff0000, v6
	v_mul_f32_e32 v48, v50, v50
	v_lshlrev_b32_e32 v58, 16, v7
	v_pk_fma_f32 v[52:53], v[50:51], v[50:51], v[48:49] op_sel_hi:[1,1,0]
	v_and_b32_e32 v59, 0xffff0000, v7
	v_mul_f32_e32 v48, v58, v58
	v_mov_b32_e32 v41, v37
	v_mov_b32_e32 v66, v40
	v_mov_b32_e32 v67, v43
	v_and_b32_e32 v68, 0xffff0000, v8
	v_lshlrev_b32_e32 v69, 16, v9
	v_and_b32_e32 v74, 0xffff0000, v9
	v_pk_fma_f32 v[60:61], v[58:59], v[58:59], v[48:49] op_sel_hi:[1,1,0]
	v_pk_mul_f32 v[66:67], v[40:41], v[66:67]
	v_pk_add_f32 v[36:37], v[36:37], v[42:43]
	v_mul_f32_e32 v48, v68, v68
	v_mul_f32_e32 v52, v69, v69
	v_mul_f32_e32 v60, v74, v74
	v_mov_b32_e32 v67, v37
	v_pk_add_f32 v[36:37], v[66:67], v[48:49]
	v_pk_add_f32 v[42:43], v[52:53], v[60:61]
	v_mov_b32_e32 v49, v145
	v_pk_add_f32 v[36:37], v[36:37], v[42:43]
	v_mov_b32_e32 v43, v145
	v_add_f32_e32 v36, v36, v37
	ds_bpermute_b32 v37, v175, v36
	v_mov_b32_e32 v48, v145
	v_mov_b32_e32 v53, v145
	v_mov_b32_e32 v52, v145
	v_mov_b32_e32 v61, v145
	s_waitcnt lgkmcnt(0)
	v_add_f32_e32 v36, v36, v37
	ds_bpermute_b32 v37, v173, v36
	v_mov_b32_e32 v60, v145
	v_mov_b32_e32 v67, v145
	v_mov_b32_e32 v66, v145
	v_mov_b32_e32 v77, v145
	s_waitcnt lgkmcnt(0)
	v_add_f32_e32 v36, v36, v37
	ds_bpermute_b32 v37, v174, v36
	v_mov_b32_e32 v76, v145
	v_mov_b32_e32 v75, v145
	v_mov_b32_e32 v85, v145
	v_mov_b32_e32 v84, v145
	s_waitcnt lgkmcnt(0)
	v_add_f32_e32 v36, v36, v37
	v_fmamk_f32 v36, v36, 0x3c000000, v179
	v_cmp_gt_f32_e32 vcc, s60, v36
	v_mul_f32_e32 v37, 0x4b800000, v36
	v_mov_b32_e32 v83, v145
	v_cndmask_b32_e32 v36, v36, v37, vcc
	v_rsq_f32_e32 v36, v36
	v_mov_b32_e32 v82, v145
	v_mov_b32_e32 v89, v145
	v_mov_b32_e32 v88, v145
	v_mul_f32_e32 v37, 0x45800000, v36
	v_cndmask_b32_e32 v41, v36, v37, vcc
	v_mul_f32_e32 v34, v41, v34
	v_mul_f32_e32 v35, v41, v35
	v_cvt_pk_bf16_f32 v34, v34, v35
	v_mul_f32_e32 v35, v41, v38
	v_mul_f32_e32 v36, v41, v39
	v_cvt_pk_bf16_f32 v35, v35, v36
	v_mul_f32_e32 v36, v41, v44
	v_mul_f32_e32 v37, v41, v46
	v_cvt_pk_bf16_f32 v36, v36, v37
	v_mul_f32_e32 v37, v41, v45
	v_mul_f32_e32 v38, v41, v47
	v_cvt_pk_bf16_f32 v37, v37, v38
	v_mul_f32_e32 v38, v41, v50
	v_mul_f32_e32 v39, v41, v51
	v_cvt_pk_bf16_f32 v38, v38, v39
	v_mul_f32_e32 v39, v41, v58
	v_mul_f32_e32 v42, v41, v59
	v_cvt_pk_bf16_f32 v39, v39, v42
	v_mul_f32_e32 v40, v41, v40
	v_mul_f32_e32 v42, v41, v68
	v_cvt_pk_bf16_f32 v40, v40, v42
	v_mul_f32_e32 v42, v41, v69
	v_mul_f32_e32 v41, v41, v74
	v_cvt_pk_bf16_f32 v41, v42, v41
	v_add_u32_e32 v42, 0, v115
	ds_write_b128 v42, v[34:37]
	ds_write_b128 v42, v[38:41] offset:8192
	v_add_u32_e32 v34, 0, v127
	ds_write_b128 v34, v[10:13] offset:16384
	v_add_u32_e32 v34, 0, v129
	ds_write_b128 v34, v[14:17] offset:16384
	v_mov_b32_e32 v37, v145
	v_mov_b32_e32 v36, v145
	v_mov_b32_e32 v35, v145
	v_mov_b32_e32 v34, v145
	v_mov_b32_e32 v41, v145
	v_mov_b32_e32 v40, v145
	v_mov_b32_e32 v39, v145
	v_mov_b32_e32 v38, v145
	v_mov_b32_e32 v45, v145
	v_mov_b32_e32 v44, v145
	v_mov_b32_e32 v42, v145
	v_mov_b32_e32 v47, v145
	v_mov_b32_e32 v46, v145
	v_mov_b32_e32 v51, v145
	v_mov_b32_e32 v50, v145
	v_mov_b32_e32 v59, v145
	v_mov_b32_e32 v58, v145
	v_mov_b32_e32 v69, v145
	v_mov_b32_e32 v68, v145
	v_mov_b32_e32 v74, v145
	v_mov_b32_e32 v87, v145
	v_mov_b32_e32 v86, v145
	v_mov_b32_e32 v93, v145
	v_mov_b32_e32 v92, v145
	v_mov_b32_e32 v91, v145
	v_mov_b32_e32 v90, v145
	v_mov_b32_e32 v97, v145
	v_mov_b32_e32 v96, v145
	v_mov_b32_e32 v95, v145
	v_mov_b32_e32 v94, v145
	v_mov_b32_e32 v101, v145
	v_mov_b32_e32 v100, v145
	v_mov_b32_e32 v99, v145
	v_mov_b32_e32 v98, v145
	v_mov_b32_e32 v109, v145
	v_mov_b32_e32 v108, v145
	v_mov_b32_e32 v110, v145
	s_waitcnt lgkmcnt(0)
	s_barrier
	s_cbranch_scc1 .LBB0_501
	s_and_b32 s80, s63, 15
	s_add_i32 s59, s58, 11
	s_add_i32 s58, s58, 12
	s_lshl_b32 s81, s80, 2
	s_cmp_gt_u32 s81, 4
	s_cselect_b32 s81, s81, 4
	s_lshl_b32 s82, s81, 7
	s_add_u32 s82, s68, s82
	s_addc_u32 s83, s69, 0
	s_add_u32 s52, s82, s52
	s_addc_u32 s53, s83, s53
	v_max_i32_e32 v34, 4, v146
	v_lshl_add_u64 v[146:147], s[52:53], 0, v[116:117]
	s_lshl_b64 s[36:37], s[36:37], 26
	s_lshl_b32 s52, s81, 20
	s_or_b32 s36, s36, s52
	s_lshl_b32 s52, s63, 4
	s_and_b32 s52, s52, 0x1f00
	s_or_b32 s36, s36, s52
	v_add_u32_e32 v34, -4, v34
	v_lshl_add_u64 v[148:149], v[132:133], 0, s[36:37]
	s_mul_i32 s36, s46, 0x7c
	s_mulk_i32 s80, 0x1f0
	v_min_u32_e32 v135, 56, v34
	s_sub_i32 s36, s36, s80
	v_mov_b32_e32 v110, 0
	v_add_u32_e32 v180, 7, v135
	v_add_u32_e32 v116, s36, v177
	s_mov_b32 s80, 0
	s_mov_b32 s63, 0
	v_mov_b32_e32 v111, v110
	v_mov_b32_e32 v112, v110
	v_mov_b32_e32 v113, v110
	v_mov_b32_e32 v106, v110
	v_mov_b32_e32 v107, v110
	v_mov_b32_e32 v108, v110
	v_mov_b32_e32 v109, v110
	v_mov_b32_e32 v102, v110
	v_mov_b32_e32 v103, v110
	v_mov_b32_e32 v104, v110
	v_mov_b32_e32 v105, v110
	v_mov_b32_e32 v98, v110
	v_mov_b32_e32 v99, v110
	v_mov_b32_e32 v100, v110
	v_mov_b32_e32 v101, v110
	v_mov_b32_e32 v94, v110
	v_mov_b32_e32 v95, v110
	v_mov_b32_e32 v96, v110
	v_mov_b32_e32 v97, v110
	v_mov_b32_e32 v90, v110
	v_mov_b32_e32 v91, v110
	v_mov_b32_e32 v92, v110
	v_mov_b32_e32 v93, v110
	v_mov_b32_e32 v86, v110
	v_mov_b32_e32 v87, v110
	v_mov_b32_e32 v88, v110
	v_mov_b32_e32 v89, v110
	v_mov_b32_e32 v82, v110
	v_mov_b32_e32 v83, v110
	v_mov_b32_e32 v84, v110
	v_mov_b32_e32 v85, v110
	v_mov_b32_e32 v74, v110
	v_mov_b32_e32 v75, v110
	v_mov_b32_e32 v76, v110
	v_mov_b32_e32 v77, v110
	v_mov_b32_e32 v66, v110
	v_mov_b32_e32 v67, v110
	v_mov_b32_e32 v68, v110
	v_mov_b32_e32 v69, v110
	v_mov_b32_e32 v58, v110
	v_mov_b32_e32 v59, v110
	v_mov_b32_e32 v60, v110
	v_mov_b32_e32 v61, v110
	v_mov_b32_e32 v50, v110
	v_mov_b32_e32 v51, v110
	v_mov_b32_e32 v52, v110
	v_mov_b32_e32 v53, v110
	v_mov_b32_e32 v46, v110
	v_mov_b32_e32 v47, v110
	v_mov_b32_e32 v48, v110
	v_mov_b32_e32 v49, v110
	v_mov_b32_e32 v42, v110
	v_mov_b32_e32 v43, v110
	v_mov_b32_e32 v44, v110
	v_mov_b32_e32 v45, v110
	v_mov_b32_e32 v38, v110
	v_mov_b32_e32 v39, v110
	v_mov_b32_e32 v40, v110
	v_mov_b32_e32 v41, v110
	v_mov_b32_e32 v34, v110
	v_mov_b32_e32 v35, v110
	v_mov_b32_e32 v36, v110
	v_mov_b32_e32 v37, v110
	v_mov_b32_e32 v144, v110
	v_mov_b32_e32 v145, v110
	s_cmp_ge_i32 s63, s59
	s_cselect_b64 s[52:53], -1, 0
	s_and_b64 vcc, exec, s[52:53]
	s_cbranch_vccnz .LBB0_512
	s_branch .LBB0_511
